# P2->P3 seam polls only the 4 producer workgroups of the row panel; full XCC poll deferred to the mid step after the first branch GEMM
# speedup vs baseline: 1.0124x; 1.0059x over previous
; __device__ __forceinline__ unsigned xb_ld(unsigned* p)              { return __hip_atomic_load(p, __ATOMIC_RELAXED, __HIP_MEMORY_SCOPE_AGENT); }
; __device__ __forceinline__ unsigned xb_add(unsigned* p, unsigned v) { return __hip_atomic_fetch_add(p, v, __ATOMIC_RELAXED, __HIP_MEMORY_SCOPE_AGENT); }
; #define XB_SPIN(cond, bar) do { unsigned _sp = 0; while (cond) { __builtin_amdgcn_s_sleep(1); \
;     if ((++_sp & 255u) == 0u) { if (xb_ld(&(bar)[XB_TMO])) break; if (_sp > XB_SPIN_CAP) { atomicAdd(&(bar)[XB_TMO], 1u); break; } } } } while (0)
; __device__ __forceinline__ bool is_t0(int wave) { return wave == 0 && olane() == 0; }
; __device__ __forceinline__ void xcdl_barrier(const XcdBarrier& b) {
;     asm volatile("s_waitcnt vmcnt(0)" ::: "memory");
;     __syncthreads();
;     if (is_t0(b.wave)) {
;         unsigned* bar = b.bar; asm volatile("" : "+s"(bar));
;         __builtin_amdgcn_s_waitcnt(0);
;         const unsigned old = xb_add(&bar[XB_LSUB(b.x)], 1u);
;         const unsigned gen = old >> 5;
;         if ((old & 31u) == 31u) xb_add(&bar[XB_LGEN(b.x)], 1u);
;         else XB_SPIN(xb_ld(&bar[XB_LGEN(b.x)]) == gen, bar);
;         __builtin_amdgcn_fence(__ATOMIC_ACQUIRE, "agent");
;         asm volatile("s_waitcnt vmcnt(0)" ::: "memory");
;     }
;     __syncthreads();
; }
.LBB0_611:
	s_and_b64 vcc, exec, s[0:1]
	s_cbranch_vccz .LBB0_631
	s_waitcnt vmcnt(0)
	s_and_b64 vcc, exec, s[46:47]
	s_waitcnt vmcnt(0)
	s_barrier
	s_cbranch_vccnz .LBB0_630
	v_mbcnt_lo_u32_b32 v0, -1, 0
	v_mbcnt_hi_u32_b32 v0, -1, v0
	s_nop 0
	v_cmp_eq_u32_e32 vcc, 0, v0
	s_and_saveexec_b64 s[4:5], vcc
	s_cbranch_execz .LBB0_629
	s_lshl_b32 s6, s23, 1
	s_add_u32 s0, s26, 0x6000
	s_addc_u32 s1, s27, 0
	s_add_u32 s0, s0, s6
	s_addc_u32 s1, s1, 0
	v_readlane_b32 s6, v254, 49
	s_add_i32 s7, s34, 2
	s_lshr_b32 s6, s6, 3
	s_lshl_b32 s6, s6, 2
	v_mov_b32_e32 v0, s6
	v_mov_b32_e32 v1, s7
	s_waitcnt vmcnt(0) lgkmcnt(0)
	global_store_dword v0, v1, s[0:1]
	s_mov_b64 s[10:11], exec
	s_and_b32 s8, s6, 28
	s_lshl_b32 exec_lo, 15, s8
	s_mov_b32 exec_hi, 0
	v_mbcnt_lo_u32_b32 v2, -1, 0
	v_lshlrev_b32_e32 v2, 2, v2
	v_mov_b32_e32 v1, s7
	s_mov_b32 s8, 0

; __device__ __forceinline__ unsigned xb_ld(unsigned* p)              { return __hip_atomic_load(p, __ATOMIC_RELAXED, __HIP_MEMORY_SCOPE_AGENT); }
; __device__ __forceinline__ unsigned xb_add(unsigned* p, unsigned v) { return __hip_atomic_fetch_add(p, v, __ATOMIC_RELAXED, __HIP_MEMORY_SCOPE_AGENT); }
; #define XB_SPIN(cond, bar) do { unsigned _sp = 0; while (cond) { __builtin_amdgcn_s_sleep(1); \
;     if ((++_sp & 255u) == 0u) { if (xb_ld(&(bar)[XB_TMO])) break; if (_sp > XB_SPIN_CAP) { atomicAdd(&(bar)[XB_TMO], 1u); break; } } } } while (0)
; __device__ __forceinline__ bool is_t0(int wave) { return wave == 0 && olane() == 0; }
; __device__ __forceinline__ void xcdl_barrier(const XcdBarrier& b) {
;     asm volatile("s_waitcnt vmcnt(0)" ::: "memory");
;     __syncthreads();
;     if (is_t0(b.wave)) {
;         unsigned* bar = b.bar; asm volatile("" : "+s"(bar));
;         __builtin_amdgcn_s_waitcnt(0);
;         const unsigned old = xb_add(&bar[XB_LSUB(b.x)], 1u);
;         const unsigned gen = old >> 5;
;         if ((old & 31u) == 31u) xb_add(&bar[XB_LGEN(b.x)], 1u);
;         else XB_SPIN(xb_ld(&bar[XB_LGEN(b.x)]) == gen, bar);
;         __builtin_amdgcn_fence(__ATOMIC_ACQUIRE, "agent");
;         asm volatile("s_waitcnt vmcnt(0)" ::: "memory");
;     }
;     __syncthreads();
; }
.Lxbf_done_S2:
	buffer_inv sc1
	s_waitcnt vmcnt(0)
	s_mov_b64 exec, s[10:11]
	s_branch .Lxbf_end_S2
	s_nop 0
	s_nop 0
	s_nop 0
	s_nop 0
	s_nop 0
	s_nop 0
	s_nop 0
	s_nop 0
	s_nop 0
	s_nop 0
	s_nop 0
	s_nop 0
	s_nop 0
	s_nop 0
	s_nop 0
	s_nop 0
	s_nop 0
	s_nop 0
	s_nop 0
	s_nop 0
	s_nop 0
	s_nop 0
	s_nop 0
	s_nop 0
	s_nop 0
	s_nop 0
	s_nop 0
	s_nop 0
	s_nop 0
	s_nop 0
	s_nop 0
	s_nop 0
	s_nop 0
	s_nop 0
	s_nop 0
	s_nop 0
	s_nop 0
	s_nop 0
	s_nop 0
	s_nop 0
	s_nop 0
	s_nop 0
	s_nop 0
	s_nop 0
	s_nop 0
	s_nop 0
	s_nop 0
	s_nop 0
	s_nop 0
	s_nop 0
	s_nop 0
	s_nop 0
	s_nop 0
	s_nop 0
	s_nop 0
	s_nop 0
	s_nop 0
	s_nop 0
	s_nop 0
	s_nop 0
	s_nop 0
	s_nop 0
	s_nop 0
	s_nop 0
	s_nop 0
	s_nop 0
	s_nop 0
	s_nop 0
	s_nop 0
	s_nop 0
	s_nop 0
	s_nop 0
	s_nop 0
	s_nop 0
	s_nop 0
	s_nop 0
	s_nop 0
	s_nop 0
	s_nop 0
	s_nop 0
	s_nop 0
	s_nop 0
	s_nop 0
	s_nop 0
	s_nop 0
	s_nop 0
	s_nop 0
	s_nop 0
	s_nop 0
	s_nop 0
	s_nop 0
	s_nop 0
	s_nop 0
	s_nop 0
	s_nop 0
	s_nop 0
	s_nop 0
	s_nop 0
	s_nop 0
	s_nop 0
	s_nop 0
	s_nop 0
	s_nop 0
	s_nop 0
	s_nop 0
	s_nop 0
	s_nop 0
	s_nop 0
.Lxbf_end_S2:
.LBB0_629:
	s_or_b64 exec, exec, s[4:5]

; #define GAS __attribute__((address_space(1)))
; __device__ __forceinline__ unsigned xb_ld(unsigned* p)              { return __hip_atomic_load(p, __ATOMIC_RELAXED, __HIP_MEMORY_SCOPE_AGENT); }
; #define XB_SPIN(cond, bar) do { unsigned _sp = 0; while (cond) { __builtin_amdgcn_s_sleep(1); \
;     if ((++_sp & 255u) == 0u) { if (xb_ld(&(bar)[XB_TMO])) break; if (_sp > XB_SPIN_CAP) { atomicAdd(&(bar)[XB_TMO], 1u); break; } } } } while (0)
; __device__ __forceinline__ bool is_t0(int wave) { return wave == 0 && olane() == 0; }
; __device__ __forceinline__ void xcdl_wait_t0(const XcdBarrier& b) {
;     if (is_t0(b.wave)) {
;         unsigned* bar = b.bar; asm volatile("" : "+s"(bar));
;         const unsigned gen = b.st[5];
;         XB_SPIN(xb_ld(&bar[XB_LGEN(b.x)]) == gen, bar);
;         __builtin_amdgcn_fence(__ATOMIC_ACQUIRE, "agent");
;         asm volatile("s_waitcnt vmcnt(0)" ::: "memory");
;     }
; }
;     __device__ __forceinline__ void mid(Acc& acc, const GUnit& u, int wr, int wc, int fr, int fq) const {
;         const int wl = ((wr * 4 + wc) * 64 + fq * 16 + fr) * 32;
;         const int bra = (u.kind == 0) ? 2 : u.kind - 1, brb = u.kind;
;         const unsigned char* Ga = MG8 + ((size_t)u.pm * 12 + bra * 4 + u.pn) * 65536 + wl; const unsigned char* Gb = MG8 + ((size_t)u.pm * 12 + brb * 4 + u.pn) * 65536 + wl;
; #pragma unroll
;         for (int ai = 0; ai < 2; ++ai)
; #pragma unroll
;             for (int bj = 0; bj < 2; ++bj) {
;                 const u32x4 a0 = *(const GAS u32x4*)(Ga + (ai * 2 + bj) * 16384), a1 = *(const GAS u32x4*)(Ga + (ai * 2 + bj) * 16384 + 16), b0 = *(const GAS u32x4*)(Gb + (ai * 2 + bj) * 16384), b1 = *(const GAS u32x4*)(Gb + (ai * 2 + bj) * 16384 + 16);
.LBB0_655:
	s_cmp_lg_u32 s33, 0
	s_cbranch_scc1 .Lsd2_done
	s_and_b64 vcc, exec, s[46:47]
	s_cbranch_vccnz .Lsd2_done
	v_readlane_b32 s90, v253, 3
	v_readlane_b32 s91, v253, 4
	s_cmp_lg_u64 s[90:91], 0
	s_cbranch_scc1 .Lsd2_done
	s_mov_b64 s[64:65], exec
	s_lshl_b32 s84, s23, 1
	s_add_u32 s90, s26, 0x6000
	s_addc_u32 s91, s27, 0
	s_add_u32 s90, s90, s84
	s_addc_u32 s91, s91, 0
	v_readlane_b32 s92, v254, 54
	s_mov_b32 exec_lo, -1
	s_mov_b32 exec_hi, 0
	s_add_i32 s92, s92, 2
	v_mbcnt_lo_u32_b32 v212, -1, 0
	v_lshlrev_b32_e32 v212, 2, v212
	v_mov_b32_e32 v213, s92
	s_mov_b32 s93, 0
.Lsd2_poll:
	global_load_dword v214, v212, s[90:91] sc1
	s_waitcnt vmcnt(0)
	v_cmp_lt_u32_e32 vcc, v214, v213
	s_nop 1
	s_cmp_eq_u64 vcc, 0
	s_cbranch_scc1 .Lsd2_ok
	s_sleep 1
	s_add_u32 s93, s93, 1
	s_cmp_lt_u32 s93, 0x4000
	s_cbranch_scc1 .Lsd2_poll
	v_mov_b32_e32 v214, 1
	v_mov_b32_e32 v212, 0x200
	global_store_dword v212, v214, s[26:27] sc1
.Lsd2_ok:
	s_waitcnt vmcnt(0)
	s_mov_b64 exec, s[64:65]
.Lsd2_done:
	s_nop 0
	s_nop 0
	s_lshl_b32 s16, s33, 2
	s_add_i32 s0, s16, -4
	s_cmp_lg_u32 s33, 0
	s_cselect_b32 s0, s0, 8
	s_ashr_i32 s1, s0, 31
	s_ashr_i32 s17, s86, 31
	s_add_u32 s18, s50, s86
	s_addc_u32 s9, s9, s17
	s_add_u32 s0, s18, s0
	s_addc_u32 s1, s9, s1
	s_lshl_b64 s[0:1], s[0:1], 16
	v_lshl_add_u64 v[128:129], v[202:203], 0, s[0:1]
	s_ashr_i32 s1, s16, 31
	s_add_u32 s0, s18, s16
	s_addc_u32 s1, s9, s1
	s_lshl_b64 s[0:1], s[0:1], 16
	v_lshl_add_u64 v[132:133], v[202:203], 0, s[0:1]
	s_movk_i32 s0, 0x4000
	v_add_co_u32_e32 v134, vcc, s0, v128
	s_mov_b64 s[16:17], 0x4000
	s_nop 0
	v_addc_co_u32_e32 v135, vcc, 0, v129, vcc
	global_load_dwordx4 v[176:179], v[128:129], off offset:16
	global_load_dwordx4 v[184:187], v[128:129], off
	global_load_dwordx4 v[180:183], v[132:133], off offset:16
	global_load_dwordx4 v[188:191], v[132:133], off
	v_lshl_add_u64 v[130:131], v[128:129], 0, s[16:17]
	global_load_dwordx4 v[168:171], v[134:135], off
	global_load_dwordx4 v[160:163], v[130:131], off offset:16
	v_add_co_u32_e32 v134, vcc, s0, v132
	v_lshl_add_u64 v[130:131], v[132:133], 0, s[16:17]
	s_nop 0
	v_addc_co_u32_e32 v135, vcc, 0, v133, vcc
	global_load_dwordx4 v[172:175], v[134:135], off
	global_load_dwordx4 v[164:167], v[130:131], off offset:16
	v_add_co_u32_e32 v134, vcc, s58, v128
	s_mov_b64 s[0:1], 0x8000
	s_nop 0
	v_addc_co_u32_e32 v135, vcc, 0, v129, vcc
	v_lshl_add_u64 v[130:131], v[128:129], 0, s[0:1]
	global_load_dwordx4 v[152:155], v[134:135], off
	global_load_dwordx4 v[144:147], v[130:131], off offset:16
	v_add_co_u32_e32 v134, vcc, s58, v132
	v_lshl_add_u64 v[130:131], v[132:133], 0, s[0:1]
	s_nop 0
	v_addc_co_u32_e32 v135, vcc, 0, v133, vcc
	s_mov_b64 s[0:1], 0xc000
	global_load_dwordx4 v[156:159], v[134:135], off
	global_load_dwordx4 v[148:151], v[130:131], off offset:16
	v_lshl_add_u64 v[130:131], v[128:129], 0, s[0:1]
	v_add_co_u32_e32 v128, vcc, 0xc000, v128
	v_lshl_add_u64 v[134:135], v[132:133], 0, s[0:1]
	s_nop 0
	v_addc_co_u32_e32 v129, vcc, 0, v129, vcc
	v_add_co_u32_e32 v132, vcc, 0xc000, v132
	global_load_dwordx4 v[136:139], v[128:129], off
	s_nop 0
	global_load_dwordx4 v[128:131], v[130:131], off offset:16
	v_addc_co_u32_e32 v133, vcc, 0, v133, vcc
	global_load_dwordx4 v[140:143], v[132:133], off
	s_nop 0
	global_load_dwordx4 v[132:135], v[134:135], off offset:16
	s_andn2_b64 vcc, exec, s[28:29]
	s_cbranch_vccnz .LBB0_636
	s_barrier
	s_branch .LBB0_636
